# P0 row-rmsnorm loop: the eight loop-invariant g_mix gain vectors are loaded once before the loop instead of a load plus full memory wait between every pair of stores
# speedup vs baseline: 1.0124x; 1.0027x over previous
; __device__ __forceinline__ unsigned pk2(float lo, float hi) { return f2bf(lo) | (f2bf(hi) << 16); }
; __device__ __forceinline__ void rms_row_to_bf16(const float* xrow, const float* g, bf16* orow, int lane) {
;     const f32x4* xr = (const f32x4*)xrow + lane; const f32x4* gr = (const f32x4*)g + lane;
;     f32x4 v[8]; float s = 0.f;
; #pragma unroll
;     for (int j = 0; j < 8; ++j) { v[j] = __builtin_nontemporal_load(xr + 64 * j); s += (v[j].x * v[j].x + v[j].y * v[j].y) + (v[j].z * v[j].z + v[j].w * v[j].w); }
;     const float rstd = rsqrtf(wave_sum(s) * (1.0f / 2048.0f) + 1e-6f);
;     unsigned long long* o8 = (unsigned long long*)orow + lane;
; #pragma unroll
;     for (int j = 0; j < 8; ++j) { const f32x4 gg = gr[64 * j];
;         o8[64 * j] = (unsigned long long)pk2(v[j].x * rstd * gg.x, v[j].y * rstd * gg.y) | ((unsigned long long)pk2(v[j].z * rstd * gg.z, v[j].w * rstd * gg.w) << 32); }
; }
; __global__ void __launch_bounds__(NWAVES * 64, 2) fwd(Params P) {
;     ...
;         for (int m = gw; m < NTOK; m += NGW) rms_row_to_bf16(x + (size_t)m * D, g_mix, UB + (size_t)m * D, lane);
.LBB0_66:
	s_cmpk_gt_i32 s4, 0x3fff
	s_cbranch_scc1 .LBB0_69
	v_mbcnt_lo_u32_b32 v2, -1, 0
	v_mbcnt_hi_u32_b32 v2, -1, v2
	v_and_b32_e32 v3, 64, v2
	v_add_u32_e32 v3, 64, v3
	v_xor_b32_e32 v4, 1, v2
	v_cmp_lt_i32_e32 vcc, v4, v3
	v_lshlrev_b32_e32 v0, 4, v154
	v_mov_b32_e32 v1, 0
	v_cndmask_b32_e32 v4, v2, v4, vcc
	v_lshlrev_b32_e32 v38, 2, v4
	v_xor_b32_e32 v4, 2, v2
	v_cmp_lt_i32_e32 vcc, v4, v3
	v_lshl_add_u64 v[24:25], s[56:57], 0, v[0:1]
	s_mov_b64 s[18:19], 0x1400
	v_cndmask_b32_e32 v4, v2, v4, vcc
	v_lshlrev_b32_e32 v39, 2, v4
	v_xor_b32_e32 v4, 4, v2
	v_cmp_lt_i32_e32 vcc, v4, v3
	v_lshl_add_u64 v[28:29], v[24:25], 0, s[18:19]
	s_mov_b64 s[18:19], 0x1800
	v_cndmask_b32_e32 v4, v2, v4, vcc
	v_lshlrev_b32_e32 v40, 2, v4
	v_xor_b32_e32 v4, 8, v2
	v_cmp_lt_i32_e32 vcc, v4, v3
	v_lshl_add_u64 v[30:31], v[24:25], 0, s[18:19]
	s_mov_b64 s[18:19], 0x1c00
	v_cndmask_b32_e32 v4, v2, v4, vcc
	v_lshlrev_b32_e32 v41, 2, v4
	v_xor_b32_e32 v4, 16, v2
	v_cmp_lt_i32_e32 vcc, v4, v3
	s_ashr_i32 s5, s4, 31
	v_lshl_add_u64 v[32:33], v[24:25], 0, s[18:19]
	v_cndmask_b32_e32 v4, v2, v4, vcc
	v_lshlrev_b32_e32 v42, 2, v4
	v_xor_b32_e32 v4, 32, v2
	s_lshl_b64 s[18:19], s[4:5], 13
	v_cmp_lt_i32_e32 vcc, v4, v3
	s_add_u32 s18, s52, s18
	s_addc_u32 s19, s53, s19
	v_cndmask_b32_e32 v2, v2, v4, vcc
	v_lshlrev_b32_e32 v43, 2, v2
	s_mov_b64 s[0:1], 0x1000
	v_lshl_add_u64 v[2:3], s[18:19], 0, v[0:1]
	s_ashr_i32 s17, s16, 31
	v_lshl_add_u64 v[26:27], v[24:25], 0, s[0:1]
	v_lshl_add_u64 v[34:35], v[2:3], 0, s[0:1]
	s_lshl_b64 s[18:19], s[16:17], 13
	s_lshl_b64 s[0:1], s[4:5], 12
	s_add_u32 s0, s86, s0
	v_lshlrev_b32_e32 v0, 3, v154
	s_addc_u32 s1, s87, s1
	v_lshl_add_u64 v[0:1], s[0:1], 0, v[0:1]
	s_mov_b64 s[0:1], 0xa161000
	v_lshl_add_u64 v[36:37], v[0:1], 0, s[0:1]
	s_lshl_b64 s[20:21], s[16:17], 12
	v_mov_b32_e32 v44, 0x358637bd
	s_mov_b32 s0, 0x800000
	s_movk_i32 s1, 0x7fff
	s_mov_b32 s5, 0xffff0000
	global_load_dwordx4 v[188:191], v[24:25], off
	global_load_dwordx4 v[192:195], v[24:25], off offset:1024
	global_load_dwordx4 v[196:199], v[24:25], off offset:2048
	global_load_dwordx4 v[200:203], v[24:25], off offset:3072
	global_load_dwordx4 v[204:207], v[26:27], off
	global_load_dwordx4 v[208:211], v[28:29], off
	global_load_dwordx4 v[212:215], v[30:31], off
	global_load_dwordx4 v[216:219], v[32:33], off
.LBB0_68:
	global_load_dwordx4 v[46:49], v[34:35], off offset:-4096 nt
	global_load_dwordx4 v[50:53], v[34:35], off offset:-3072 nt
	global_load_dwordx4 v[20:23], v[34:35], off offset:-2048 nt
	global_load_dwordx4 v[12:15], v[34:35], off nt
	global_load_dwordx4 v[16:19], v[34:35], off offset:-1024 nt
	global_load_dwordx4 v[8:11], v[34:35], off offset:1024 nt
	global_load_dwordx4 v[0:3], v[34:35], off offset:3072 nt
	global_load_dwordx4 v[4:7], v[34:35], off offset:2048 nt
	s_add_i32 s4, s4, s16
	v_lshl_add_u64 v[34:35], v[34:35], 0, s[18:19]
	s_cmpk_gt_i32 s4, 0x3fff
	s_waitcnt vmcnt(7)
	v_mov_b32_e32 v60, v47
	s_waitcnt vmcnt(6)
	v_mov_b32_e32 v61, v51
	v_mov_b32_e32 v64, v49
	v_mov_b32_e32 v65, v53
	v_mov_b32_e32 v58, v46
	v_mov_b32_e32 v59, v50
	v_mov_b32_e32 v62, v48
	v_mov_b32_e32 v63, v52
	s_waitcnt vmcnt(5)
	v_pk_mul_f32 v[66:67], v[22:23], v[22:23]
	v_pk_mul_f32 v[68:69], v[20:21], v[20:21]
	v_pk_mul_f32 v[60:61], v[60:61], v[60:61]
	v_pk_mul_f32 v[64:65], v[64:65], v[64:65]
	v_pk_mov_b32 v[82:83], v[68:69], v[66:67] op_sel:[1,0]
	v_mov_b32_e32 v69, v67
	v_pk_fma_f32 v[58:59], v[58:59], v[58:59], v[60:61]
	v_pk_fma_f32 v[60:61], v[62:63], v[62:63], v[64:65]
	s_waitcnt vmcnt(3)
	v_mul_f32_e32 v70, v17, v17
	v_mul_f32_e32 v72, v19, v19
	v_pk_add_f32 v[62:63], v[82:83], v[68:69]
	v_pk_add_f32 v[58:59], v[58:59], v[60:61]
	v_mul_f32_e32 v45, v12, v12
	v_mul_f32_e32 v81, v13, v13
	v_mul_f32_e32 v84, v14, v14
	v_mul_f32_e32 v85, v15, v15
	v_pk_fma_f32 v[66:67], v[16:17], v[16:17], v[70:71] op_sel_hi:[1,1,0]
	v_pk_fma_f32 v[70:71], v[18:19], v[18:19], v[72:73] op_sel_hi:[1,1,0]
	v_pk_add_f32 v[60:61], v[62:63], v[62:63] op_sel:[0,1] op_sel_hi:[1,0]
	v_pk_add_f32 v[58:59], v[58:59], v[58:59] op_sel:[0,1] op_sel_hi:[1,0]
	s_waitcnt vmcnt(2)
	v_pk_mul_f32 v[74:75], v[10:11], v[10:11]
	v_pk_mul_f32 v[76:77], v[8:9], v[8:9]
	v_mov_b32_e32 v67, v84
	v_mov_b32_e32 v71, v85
	v_mov_b32_e32 v61, v81
	v_mov_b32_e32 v59, v45
	v_pk_mov_b32 v[72:73], v[76:77], v[74:75] op_sel:[1,0]
	v_mov_b32_e32 v77, v75
	v_pk_add_f32 v[62:63], v[66:67], v[70:71]
	v_pk_add_f32 v[58:59], v[58:59], v[60:61]
	s_waitcnt vmcnt(0)
	v_mul_f32_e32 v78, v5, v5
	v_mul_f32_e32 v80, v7, v7
	v_pk_add_f32 v[64:65], v[72:73], v[76:77]
	v_pk_add_f32 v[58:59], v[58:59], v[62:63]
	v_mul_f32_e32 v86, v0, v0
	v_mul_f32_e32 v87, v1, v1
	v_mul_f32_e32 v88, v2, v2
	v_mul_f32_e32 v89, v3, v3
	v_pk_fma_f32 v[74:75], v[4:5], v[4:5], v[78:79] op_sel_hi:[1,1,0]
	v_pk_fma_f32 v[78:79], v[6:7], v[6:7], v[80:81] op_sel_hi:[1,1,0]
	v_pk_add_f32 v[64:65], v[64:65], v[64:65] op_sel:[0,1] op_sel_hi:[1,0]
	v_pk_add_f32 v[58:59], v[58:59], v[58:59] op_sel:[0,1] op_sel_hi:[1,0]
	v_mov_b32_e32 v75, v88
	v_mov_b32_e32 v79, v89
	v_mov_b32_e32 v65, v87
	v_mov_b32_e32 v59, v86
	v_pk_add_f32 v[66:67], v[74:75], v[78:79]
	v_pk_add_f32 v[58:59], v[58:59], v[64:65]
	s_nop 0
	v_pk_add_f32 v[58:59], v[58:59], v[66:67]
	s_nop 0
	v_add_f32_e32 v45, v58, v59
	ds_bpermute_b32 v58, v38, v45
	s_waitcnt lgkmcnt(0)
	v_add_f32_e32 v45, v45, v58
	ds_bpermute_b32 v58, v39, v45
	s_waitcnt lgkmcnt(0)
	v_add_f32_e32 v45, v45, v58
	ds_bpermute_b32 v58, v40, v45
	s_waitcnt lgkmcnt(0)
	v_add_f32_e32 v45, v45, v58
	ds_bpermute_b32 v58, v41, v45
	s_waitcnt lgkmcnt(0)
; __device__ __forceinline__ unsigned pk2(float lo, float hi) { return f2bf(lo) | (f2bf(hi) << 16); }
; __device__ __forceinline__ void rms_row_to_bf16(const float* xrow, const float* g, bf16* orow, int lane) {
;     const f32x4* xr = (const f32x4*)xrow + lane; const f32x4* gr = (const f32x4*)g + lane;
;     f32x4 v[8]; float s = 0.f;
; #pragma unroll
;     for (int j = 0; j < 8; ++j) { v[j] = __builtin_nontemporal_load(xr + 64 * j); s += (v[j].x * v[j].x + v[j].y * v[j].y) + (v[j].z * v[j].z + v[j].w * v[j].w); }
;     const float rstd = rsqrtf(wave_sum(s) * (1.0f / 2048.0f) + 1e-6f);
;     unsigned long long* o8 = (unsigned long long*)orow + lane;
; #pragma unroll
;     for (int j = 0; j < 8; ++j) { const f32x4 gg = gr[64 * j];
;         o8[64 * j] = (unsigned long long)pk2(v[j].x * rstd * gg.x, v[j].y * rstd * gg.y) | ((unsigned long long)pk2(v[j].z * rstd * gg.z, v[j].w * rstd * gg.w) << 32); }
; }
	v_add_f32_e32 v45, v45, v58
	ds_bpermute_b32 v58, v42, v45
	s_waitcnt lgkmcnt(0)
	v_add_f32_e32 v45, v45, v58
	ds_bpermute_b32 v58, v43, v45
	s_waitcnt lgkmcnt(0)
	v_add_f32_e32 v45, v45, v58
	v_fmamk_f32 v45, v45, 0x3a000000, v44
	v_mul_f32_e32 v58, 0x4b800000, v45
	v_cmp_gt_f32_e32 vcc, s0, v45
	s_nop 1
	v_cndmask_b32_e32 v45, v45, v58, vcc
	v_rsq_f32_e32 v45, v45
	s_nop 0
	v_mul_f32_e32 v58, 0x45800000, v45
	v_cndmask_b32_e32 v45, v45, v58, vcc
	v_mul_f32_e32 v46, v46, v45
	v_mul_f32_e32 v48, v48, v45
	v_mul_f32_e32 v47, v47, v45
	v_mul_f32_e32 v49, v49, v45
	v_mul_f32_e32 v46, v188, v46
	v_mul_f32_e32 v48, v190, v48
	v_mul_f32_e32 v47, v189, v47
	v_mul_f32_e32 v49, v191, v49
	v_bfe_u32 v54, v46, 16, 1
	v_bfe_u32 v56, v48, 16, 1
	v_bfe_u32 v55, v47, 16, 1
	v_bfe_u32 v57, v49, 16, 1
	v_add3_u32 v46, v46, v54, s1
	v_add3_u32 v48, v48, v56, s1
	v_add3_u32 v47, v47, v55, s1
	v_add3_u32 v49, v49, v57, s1
	v_lshrrev_b32_e32 v46, 16, v46
	v_lshrrev_b32_e32 v48, 16, v48
	v_and_or_b32 v46, v47, s5, v46
	v_and_or_b32 v47, v49, s5, v48
	global_store_dwordx2 v[36:37], v[46:47], off
	v_mul_f32_e32 v50, v50, v45
	v_mul_f32_e32 v52, v52, v45
	v_mul_f32_e32 v51, v51, v45
	v_mul_f32_e32 v53, v53, v45
	v_mul_f32_e32 v20, v20, v45
	v_mul_f32_e32 v22, v22, v45
	v_mul_f32_e32 v21, v21, v45
	v_mul_f32_e32 v23, v23, v45
	v_mul_f32_e32 v16, v16, v45
	v_mul_f32_e32 v18, v18, v45
	v_mul_f32_e32 v17, v17, v45
	v_mul_f32_e32 v19, v19, v45
	v_mul_f32_e32 v12, v12, v45
	v_mul_f32_e32 v14, v14, v45
	v_mul_f32_e32 v13, v13, v45
	v_mul_f32_e32 v15, v15, v45
	v_mul_f32_e32 v8, v8, v45
	v_mul_f32_e32 v10, v10, v45
	v_mul_f32_e32 v9, v9, v45
	v_mul_f32_e32 v11, v11, v45
	v_mul_f32_e32 v4, v4, v45
	v_mul_f32_e32 v6, v6, v45
	v_mul_f32_e32 v5, v5, v45
	v_mul_f32_e32 v7, v7, v45
	v_mul_f32_e32 v0, v0, v45
	v_mul_f32_e32 v2, v2, v45
	v_mul_f32_e32 v1, v1, v45
	v_mul_f32_e32 v3, v3, v45
	v_mul_f32_e32 v220, v192, v50
	v_mul_f32_e32 v222, v194, v52
	v_mul_f32_e32 v221, v193, v51
	v_mul_f32_e32 v223, v195, v53
	v_bfe_u32 v50, v220, 16, 1
	v_bfe_u32 v52, v222, 16, 1
	v_bfe_u32 v51, v221, 16, 1
	v_bfe_u32 v53, v223, 16, 1
	v_add3_u32 v220, v220, v50, s1
	v_add3_u32 v222, v222, v52, s1
	v_add3_u32 v221, v221, v51, s1
	v_add3_u32 v223, v223, v53, s1
	v_lshrrev_b32_e32 v220, 16, v220
	v_lshrrev_b32_e32 v222, 16, v222
	v_and_or_b32 v220, v221, s5, v220
	v_and_or_b32 v221, v223, s5, v222
	global_store_dwordx2 v[36:37], v[220:221], off offset:512
	v_mul_f32_e32 v20, v196, v20
	v_mul_f32_e32 v22, v198, v22
	v_mul_f32_e32 v21, v197, v21
	v_mul_f32_e32 v23, v199, v23
	v_bfe_u32 v46, v20, 16, 1
	v_bfe_u32 v48, v22, 16, 1
	v_bfe_u32 v47, v21, 16, 1
	v_bfe_u32 v49, v23, 16, 1
	v_add3_u32 v20, v20, v46, s1
	v_add3_u32 v22, v22, v48, s1
	v_add3_u32 v21, v21, v47, s1
	v_add3_u32 v23, v23, v49, s1
	v_lshrrev_b32_e32 v20, 16, v20
	v_lshrrev_b32_e32 v22, 16, v22
	v_and_or_b32 v20, v21, s5, v20
	v_and_or_b32 v21, v23, s5, v22
	global_store_dwordx2 v[36:37], v[20:21], off offset:1024
	v_mul_f32_e32 v16, v200, v16
	v_mul_f32_e32 v18, v202, v18
	v_mul_f32_e32 v17, v201, v17
	v_mul_f32_e32 v19, v203, v19
	v_bfe_u32 v20, v16, 16, 1
	v_bfe_u32 v22, v18, 16, 1
	v_bfe_u32 v21, v17, 16, 1
	v_bfe_u32 v23, v19, 16, 1
	v_add3_u32 v16, v16, v20, s1
	v_add3_u32 v18, v18, v22, s1
	v_add3_u32 v17, v17, v21, s1
	v_add3_u32 v19, v19, v23, s1
	v_lshrrev_b32_e32 v16, 16, v16
	v_lshrrev_b32_e32 v18, 16, v18
	v_and_or_b32 v16, v17, s5, v16
	v_and_or_b32 v17, v19, s5, v18
	global_store_dwordx2 v[36:37], v[16:17], off offset:1536
	v_mul_f32_e32 v12, v204, v12
	v_mul_f32_e32 v14, v206, v14
	v_mul_f32_e32 v13, v205, v13
	v_mul_f32_e32 v15, v207, v15
	v_bfe_u32 v16, v12, 16, 1
	v_bfe_u32 v18, v14, 16, 1
	v_bfe_u32 v17, v13, 16, 1
	v_bfe_u32 v19, v15, 16, 1
	v_add3_u32 v12, v12, v16, s1
	v_add3_u32 v14, v14, v18, s1
	v_add3_u32 v13, v13, v17, s1
	v_add3_u32 v15, v15, v19, s1
	v_lshrrev_b32_e32 v12, 16, v12
	v_lshrrev_b32_e32 v14, 16, v14
	v_and_or_b32 v12, v13, s5, v12
	v_and_or_b32 v13, v15, s5, v14
	global_store_dwordx2 v[36:37], v[12:13], off offset:2048
	v_mul_f32_e32 v8, v8, v208
	v_mul_f32_e32 v10, v10, v210
	v_mul_f32_e32 v9, v9, v209
	v_mul_f32_e32 v11, v11, v211
	v_bfe_u32 v12, v8, 16, 1
	v_bfe_u32 v14, v10, 16, 1
	v_bfe_u32 v13, v9, 16, 1
	v_bfe_u32 v15, v11, 16, 1
	v_add3_u32 v8, v8, v12, s1
	v_add3_u32 v10, v10, v14, s1
	v_add3_u32 v9, v9, v13, s1
	v_add3_u32 v11, v11, v15, s1
	v_lshrrev_b32_e32 v8, 16, v8
	v_lshrrev_b32_e32 v10, 16, v10
	v_and_or_b32 v8, v9, s5, v8
	v_and_or_b32 v9, v11, s5, v10
	global_store_dwordx2 v[36:37], v[8:9], off offset:2560
	v_mul_f32_e32 v4, v4, v212
	v_mul_f32_e32 v6, v6, v214
	v_mul_f32_e32 v5, v5, v213
	v_mul_f32_e32 v7, v7, v215
	v_bfe_u32 v8, v4, 16, 1
	v_bfe_u32 v10, v6, 16, 1
	v_bfe_u32 v9, v5, 16, 1
	v_bfe_u32 v11, v7, 16, 1
	v_add3_u32 v4, v4, v8, s1
	v_add3_u32 v6, v6, v10, s1
	v_add3_u32 v5, v5, v9, s1
	v_add3_u32 v7, v7, v11, s1
	v_lshrrev_b32_e32 v4, 16, v4
	v_lshrrev_b32_e32 v6, 16, v6
	v_and_or_b32 v4, v5, s5, v4
	v_and_or_b32 v5, v7, s5, v6
	global_store_dwordx2 v[36:37], v[4:5], off offset:3072
	v_mul_f32_e32 v0, v0, v216
	v_mul_f32_e32 v2, v2, v218
	v_mul_f32_e32 v1, v1, v217
	v_mul_f32_e32 v3, v3, v219
	v_bfe_u32 v4, v0, 16, 1
	v_bfe_u32 v6, v2, 16, 1
	v_bfe_u32 v5, v1, 16, 1
	v_bfe_u32 v7, v3, 16, 1
	v_add3_u32 v0, v0, v4, s1
	v_add3_u32 v2, v2, v6, s1
	v_add3_u32 v1, v1, v5, s1
	v_add3_u32 v3, v3, v7, s1
	v_lshrrev_b32_e32 v0, 16, v0
	v_lshrrev_b32_e32 v2, 16, v2
	v_and_or_b32 v0, v1, s5, v0
	v_and_or_b32 v1, v3, s5, v2
	global_store_dwordx2 v[36:37], v[0:1], off offset:3584
	v_lshl_add_u64 v[36:37], v[36:37], 0, s[20:21]
	s_cbranch_scc0 .LBB0_68
